# mixer B loop: static priority raise (s_setprio 1) for waves 4-7 for the whole loop
# speedup vs baseline: 1.0021x; 1.0021x over previous
; #define LAS __attribute__((address_space(3)))
; DI void mixerB2_unit(int u, int l, const bf16* PROJ, bf16* YC, const float* dlam_l, const float* dnw_l, const float* kmax_l, LAS char* lds, int tid, int wave, int lane) {
;     ...
;     f32x4 o1[2][4], o2[2][4], ol1[2], ol2[2];
; #pragma unroll
;     for (int qt = 0; qt < 2; ++qt) { ol1[qt] = (f32x4){0.f, 0.f, 0.f, 0.f}; ol2[qt] = ol1[qt];
; #pragma unroll
;         for (int c = 0; c < 4; ++c) { o1[qt][c] = ol1[qt]; o2[qt][c] = ol1[qt]; } }
;     const bf16x8 ones = {0x3F80, 0x3F80, 0x3F80, 0x3F80, 0x3F80, 0x3F80, 0x3F80, 0x3F80};
;     for (int kt128 = 0; kt128 < 16; ++kt128) {
;         {
;         const LAS char* K0 = Kb + (kt128 & 1) * KV_TILE; const LAS char* V0 = Vb + (kt128 & 1) * KV_TILE;
;     ...
;         SBlk SA, SB;
;         B_QK(SA, 0, 0); B_QK(SB, 0, 1);
.LBB0_254:
	s_mov_b32 s0, 0
	s_movk_i32 s1, 0x4800
	v_add_u32_e32 v232, v171, v166
	v_add_u32_e32 v250, v198, v199
	v_mov_b32_e32 v218, v232
	v_mov_b32_e32 v217, v250
	ds_read_b128 v[156:159], v213
	ds_read_b128 v[160:163], v213 offset:64
	ds_read_b128 v[242:245], v213 offset:2304
	ds_read_b128 v[246:249], v213 offset:2368
	ds_read_b128 v[140:143], v218
	ds_read_b128 v[144:147], v218 offset:64
	ds_read_b128 v[148:151], v218 offset:2304
	ds_read_b128 v[152:155], v218 offset:2368
	v_mov_b32_e32 v228, 0x3f803f80
	v_mov_b32_e32 v229, 0x3f803f80
	v_mov_b32_e32 v230, 0x3f803f80
	v_mov_b32_e32 v231, 0x3f803f80
	v_mov_b32_e32 v116, 0
	v_mov_b32_e32 v117, 0
	v_mov_b32_e32 v118, 0
	v_mov_b32_e32 v119, 0
	v_mov_b32_e32 v120, 0
	v_mov_b32_e32 v121, 0
	v_mov_b32_e32 v122, 0
	v_mov_b32_e32 v123, 0
	v_mov_b32_e32 v124, 0
	v_mov_b32_e32 v125, 0
	v_mov_b32_e32 v126, 0
	v_mov_b32_e32 v127, 0
	v_mov_b32_e32 v128, 0
	v_mov_b32_e32 v129, 0
	v_mov_b32_e32 v130, 0
	v_mov_b32_e32 v131, 0
	v_mov_b32_e32 v132, 0
	v_mov_b32_e32 v133, 0
	v_mov_b32_e32 v134, 0
	v_mov_b32_e32 v135, 0
	v_mov_b32_e32 v136, 0
	v_mov_b32_e32 v137, 0
	v_mov_b32_e32 v138, 0
	v_mov_b32_e32 v139, 0
	s_add_i32 s40, s44, s46
	s_waitcnt lgkmcnt(4)
	v_readlane_b32 s98, v253, 0
	s_nop 0
	s_cmp_lt_u32 s98, 0x100
	s_cbranch_scc1 .Lb2_top
	s_setprio 1

.Lb2_drain:
	s_setprio 0
	s_waitcnt lgkmcnt(0)
	v_mfma_f32_16x16x32_bf16 v[52:55], v[228:231], v[116:119], v[52:55]
	v_mfma_f32_16x16x32_bf16 v[48:51], v[228:231], v[120:123], v[48:51]
	v_mfma_f32_16x16x32_bf16 v[44:47], v[124:127], v[116:119], v[44:47]
	v_mfma_f32_16x16x32_bf16 v[32:35], v[124:127], v[120:123], v[32:35]
	v_mfma_f32_16x16x32_bf16 v[40:43], v[128:131], v[116:119], v[40:43]
	v_mfma_f32_16x16x32_bf16 v[24:27], v[128:131], v[120:123], v[24:27]
	v_mfma_f32_16x16x32_bf16 v[36:39], v[132:135], v[116:119], v[36:39]
	v_mfma_f32_16x16x32_bf16 v[20:23], v[132:135], v[120:123], v[20:23]
	v_mfma_f32_16x16x32_bf16 v[28:31], v[136:139], v[116:119], v[28:31]
	v_mfma_f32_16x16x32_bf16 v[16:19], v[136:139], v[120:123], v[16:19]
	s_mov_b32 s47, 0
	s_nop 7
